# grid barrier release flattened: all workgroups poll the cross-XCD generation word; per-XCD release atomic and its wait removed
# speedup vs baseline: 1.0184x; 1.0081x over previous
; __device__ __forceinline__ unsigned xb_ld(unsigned* p)              { return __hip_atomic_load(p, __ATOMIC_RELAXED, __HIP_MEMORY_SCOPE_AGENT); }
; __device__ __forceinline__ unsigned xb_add(unsigned* p, unsigned v) { return __hip_atomic_fetch_add(p, v, __ATOMIC_RELAXED, __HIP_MEMORY_SCOPE_AGENT); }
; #define XB_SPIN(cond, bar) do { unsigned _sp = 0; while (cond) { __builtin_amdgcn_s_sleep(1); \
;     if ((++_sp & 255u) == 0u) { if (xb_ld(&(bar)[XB_TMO])) break; if (_sp > XB_SPIN_CAP) { atomicAdd(&(bar)[XB_TMO], 1u); break; } } } } while (0)
; __device__ __forceinline__ void xcd_barrier(const XcdBarrier& b) {
;     ...
;         const unsigned old = xb_add(&bar[XB_XSUB(b.x)], 1u);
;         const unsigned gen = old / nloc;
;         if (old + 1u == (gen + 1u) * nloc) {
;             __builtin_amdgcn_fence(__ATOMIC_RELEASE, "agent");
;             asm volatile("s_waitcnt vmcnt(0)" ::: "memory");
;             const unsigned og = xb_add(&bar[XB_TOP], 1u);
;             const unsigned tg = og / nx;
;             if (og + 1u == (tg + 1u) * nx) xb_add(&bar[XB_TOPGEN], 1u);
;             else XB_SPIN(xb_ld(&bar[XB_TOPGEN]) == tg, bar);
;             __builtin_amdgcn_fence(__ATOMIC_ACQUIRE, "agent");
;             xb_add(&bar[XB_XGEN(b.x)], 1u);
;             asm volatile("s_waitcnt vmcnt(0)" ::: "memory");
;         } else {
;             XB_SPIN(xb_ld(&bar[XB_XGEN(b.x)]) == gen, bar);
.LBB0_40:
	s_or_b64 exec, exec, s[10:11]
	buffer_inv sc1
	v_cvt_f32_u32_e32 v5, v3
	s_waitcnt vmcnt(0)
	v_readfirstlane_b32 s3, v4
	v_sub_u32_e32 v4, 0, v3
	v_rcp_iflag_f32_e32 v5, v5
	v_add_u32_e32 v6, s3, v2
	v_mul_f32_e32 v5, 0x4f7ffffe, v5
	v_cvt_u32_f32_e32 v5, v5
	v_mul_lo_u32 v2, v4, v5
	v_mul_hi_u32 v2, v5, v2
	v_add_u32_e32 v2, v5, v2
	v_mul_hi_u32 v2, v6, v2
	v_mul_lo_u32 v4, v2, v3
	v_sub_u32_e32 v4, v6, v4
	v_add_u32_e32 v5, 1, v2
	v_sub_u32_e32 v7, v4, v3
	v_cmp_ge_u32_e32 vcc, v4, v3
	s_nop 1
	v_cndmask_b32_e32 v2, v2, v5, vcc
	v_cndmask_b32_e32 v4, v4, v7, vcc
	v_add_u32_e32 v5, 1, v2
	v_cmp_ge_u32_e32 vcc, v4, v3
	v_add_u32_e32 v4, 1, v6
	s_nop 0
	v_cndmask_b32_e32 v2, v2, v5, vcc
	v_mul_lo_u32 v5, v3, v2
	v_add_u32_e32 v3, v5, v3
	v_cmp_ne_u32_e32 vcc, v4, v3
	s_and_saveexec_b64 s[10:11], vcc
	s_xor_b64 s[10:11], exec, s[10:11]
	s_cbranch_execz .LBB0_54
	v_readlane_b32 s14, v252, 14
	v_readlane_b32 s15, v252, 15
	s_waitcnt lgkmcnt(0)
	s_nop 3
	global_load_dword v0, v1, s[14:15] sc1
	s_waitcnt vmcnt(0)
	v_cmp_eq_u32_e32 vcc, v0, v2
	s_and_saveexec_b64 s[16:17], vcc
	s_cbranch_execz .LBB0_53
	s_mov_b32 s3, 1
	s_mov_b64 s[18:19], 0
	s_branch .LBB0_44

; __device__ __forceinline__ unsigned xb_ld(unsigned* p)              { return __hip_atomic_load(p, __ATOMIC_RELAXED, __HIP_MEMORY_SCOPE_AGENT); }
; #define XB_SPIN(cond, bar) do { unsigned _sp = 0; while (cond) { __builtin_amdgcn_s_sleep(1); \
;     if ((++_sp & 255u) == 0u) { if (xb_ld(&(bar)[XB_TMO])) break; if (_sp > XB_SPIN_CAP) { atomicAdd(&(bar)[XB_TMO], 1u); break; } } } } while (0)
; __device__ __forceinline__ void xcd_barrier(const XcdBarrier& b) {
;     ...
;             XB_SPIN(xb_ld(&bar[XB_XGEN(b.x)]) == gen, bar);
.LBB0_48:
	v_readlane_b32 s14, v252, 14
	v_readlane_b32 s15, v252, 15
	s_add_i32 s3, s3, 1
	s_mov_b64 s[38:39], -1
	s_nop 2
	global_load_dword v0, v1, s[14:15] sc1
	s_waitcnt vmcnt(0)
	v_cmp_ne_u32_e32 vcc, v0, v2
	s_orn2_b64 s[36:37], vcc, exec
	s_branch .LBB0_43

; __device__ __forceinline__ unsigned xb_add(unsigned* p, unsigned v) { return __hip_atomic_fetch_add(p, v, __ATOMIC_RELAXED, __HIP_MEMORY_SCOPE_AGENT); }
; __device__ __forceinline__ void xcd_barrier(const XcdBarrier& b) {
;     ...
;             __builtin_amdgcn_fence(__ATOMIC_ACQUIRE, "agent");
;             xb_add(&bar[XB_XGEN(b.x)], 1u);
;             asm volatile("s_waitcnt vmcnt(0)" ::: "memory");
.LBB0_71:
	s_or_b64 exec, exec, s[10:11]
	s_mov_b64 s[10:11], exec
	v_mbcnt_lo_u32_b32 v0, s10, 0
	v_mbcnt_hi_u32_b32 v0, s11, v0
	v_cmp_eq_u32_e32 vcc, 0, v0
	s_and_saveexec_b64 s[16:17], vcc
	s_cbranch_execz .LBB0_73
	s_bcnt1_i32_b64 s3, s[10:11]
	v_readlane_b32 s10, v252, 10
	v_mov_b32_e32 v0, s3
	v_readlane_b32 s11, v252, 11
	s_nop 4
